# attention loops: LDS-write and K/V prefetch addresses recomputed per trip with 64-bit vector math replaced by 32-bit v_mad_u32_u24 / v_lshl_add_u32 and SGPR-base global loads (5+4 LDS sites, 2 prefetc
# speedup vs baseline: 1.0010x; 1.0004x over previous
.LBB0_165:
	ds_read_b128 v[136:139], v119 offset:13824
	ds_read_b128 v[140:143], v119 offset:13856
	ds_read_b128 v[144:147], v119 offset:13888
	ds_read_b128 v[148:151], v119 offset:13920
	v_sub_f32_e32 v48, v48, v122
	v_sub_f32_e32 v32, v32, v122
	v_sub_f32_e32 v49, v49, v122
	v_sub_f32_e32 v33, v33, v122
	v_sub_f32_e32 v50, v50, v122
	v_sub_f32_e32 v34, v34, v122
	v_sub_f32_e32 v51, v51, v122
	v_sub_f32_e32 v35, v35, v122
	v_sub_f32_e32 v52, v52, v122
	v_sub_f32_e32 v36, v36, v122
	v_sub_f32_e32 v53, v53, v122
	v_sub_f32_e32 v37, v37, v122
	v_sub_f32_e32 v54, v54, v122
	v_sub_f32_e32 v38, v38, v122
	v_sub_f32_e32 v55, v55, v122
	v_sub_f32_e32 v39, v39, v122
	v_sub_f32_e32 v56, v56, v122
	v_sub_f32_e32 v40, v40, v122
	v_sub_f32_e32 v57, v57, v122
	v_sub_f32_e32 v41, v41, v122
	v_sub_f32_e32 v58, v58, v122
	v_sub_f32_e32 v42, v42, v122
	v_sub_f32_e32 v59, v59, v122
	v_sub_f32_e32 v43, v43, v122
	v_sub_f32_e32 v60, v60, v122
	v_sub_f32_e32 v44, v44, v122
	v_sub_f32_e32 v61, v61, v122
	v_sub_f32_e32 v45, v45, v122
	v_sub_f32_e32 v62, v62, v122
	v_sub_f32_e32 v46, v46, v122
	v_sub_f32_e32 v63, v63, v122
	v_sub_f32_e32 v47, v47, v122
	v_exp_f32_e32 v48, v48
	v_exp_f32_e32 v32, v32
	v_exp_f32_e32 v49, v49
	v_exp_f32_e32 v33, v33
	v_exp_f32_e32 v50, v50
	v_exp_f32_e32 v34, v34
	v_exp_f32_e32 v51, v51
	v_exp_f32_e32 v35, v35
	v_exp_f32_e32 v52, v52
	v_exp_f32_e32 v36, v36
	v_exp_f32_e32 v53, v53
	v_exp_f32_e32 v37, v37
	v_exp_f32_e32 v54, v54
	v_exp_f32_e32 v38, v38
	v_exp_f32_e32 v55, v55
	v_exp_f32_e32 v39, v39
	v_exp_f32_e32 v56, v56
	v_exp_f32_e32 v40, v40
	v_exp_f32_e32 v57, v57
	v_exp_f32_e32 v41, v41
	v_exp_f32_e32 v58, v58
	v_exp_f32_e32 v42, v42
	v_exp_f32_e32 v59, v59
	v_exp_f32_e32 v43, v43
	v_exp_f32_e32 v60, v60
	v_exp_f32_e32 v44, v44
	v_exp_f32_e32 v61, v61
	v_exp_f32_e32 v45, v45
	v_exp_f32_e32 v62, v62
	v_exp_f32_e32 v46, v46
	v_exp_f32_e32 v63, v63
	v_exp_f32_e32 v47, v47
	v_cvt_pk_bf16_f32 v124, v48, v49
	v_cvt_pk_bf16_f32 v125, v50, v51
	v_cvt_pk_bf16_f32 v126, v52, v53
	v_cvt_pk_bf16_f32 v127, v54, v55
	v_cvt_pk_bf16_f32 v128, v32, v33
	v_cvt_pk_bf16_f32 v129, v34, v35
	v_cvt_pk_bf16_f32 v130, v36, v37
	v_cvt_pk_bf16_f32 v131, v38, v39
	v_cvt_pk_bf16_f32 v132, v56, v57
	v_cvt_pk_bf16_f32 v133, v58, v59
	v_cvt_pk_bf16_f32 v134, v60, v61
	v_cvt_pk_bf16_f32 v135, v62, v63
	v_cvt_pk_bf16_f32 v152, v40, v41
	v_cvt_pk_bf16_f32 v153, v42, v43
	v_cvt_pk_bf16_f32 v154, v44, v45
	v_cvt_pk_bf16_f32 v155, v46, v47
	s_setprio 1
	s_waitcnt lgkmcnt(7)
	v_mfma_f32_32x32x16_bf16 v[16:31], v[110:113], v[124:127], v[16:31]
	s_waitcnt lgkmcnt(6)
	v_mfma_f32_32x32x16_bf16 v[16:31], v[106:109], v[132:135], v[16:31]
	s_waitcnt lgkmcnt(5)
	v_mfma_f32_32x32x16_bf16 v[16:31], v[102:105], v[128:131], v[16:31]
	s_waitcnt lgkmcnt(4)
	v_mfma_f32_32x32x16_bf16 v[16:31], v[98:101], v[152:155], v[16:31]
	s_setprio 0
	s_setprio 1
	s_waitcnt lgkmcnt(3)
	v_mfma_f32_32x32x16_bf16 v[0:15], v[136:139], v[124:127], v[0:15]
	s_waitcnt lgkmcnt(2)
	v_mfma_f32_32x32x16_bf16 v[0:15], v[140:143], v[132:135], v[0:15]
	s_waitcnt lgkmcnt(1)
	v_mfma_f32_32x32x16_bf16 v[0:15], v[144:147], v[128:131], v[0:15]
	s_waitcnt lgkmcnt(0)
	v_mfma_f32_32x32x16_bf16 v[0:15], v[148:151], v[152:155], v[0:15]
	s_setprio 0
	s_andn2_b64 vcc, exec, s[50:51]
	v_lshrrev_b32_e32 v98, 3, v204
	v_lshlrev_b32_e32 v96, 4, v204
	v_and_b32_e32 v96, 0x70, v96
	v_mad_u32_u24 v96, v98, s55, v96
	s_waitcnt vmcnt(1)
	ds_write_b128 v96, v[80:83] offset:18432
	s_waitcnt vmcnt(0)
	ds_write_b128 v96, v[84:87] offset:27648
	v_cndmask_b32_e64 v96, 0, 1, s[50:51]
	v_cmp_ne_u32_e64 s[0:1], 1, v96
	s_waitcnt lgkmcnt(0)
	s_barrier
	s_cbranch_vccnz .LBB0_167
	v_lshrrev_b32_e32 v86, 3, v204
	v_lshlrev_b32_e32 v96, 4, v204
	v_and_b32_e32 v96, 0x70, v96
	v_lshl_add_u32 v87, v86, 7, v96
	v_lshl_add_u32 v86, v86, 9, v96
	v_add_u32_e32 v87, 0x6000, v87
	s_nop 0
	global_load_dwordx4 v[80:83], v87, s[40:41]
	s_nop 0
	global_load_dwordx4 v[84:87], v86, s[48:49] offset:384

.LBB0_170:
	ds_read_b128 v[134:137], v119 offset:32256
	ds_read_b128 v[138:141], v119 offset:32288
	ds_read_b128 v[142:145], v119 offset:32320
	ds_read_b128 v[146:149], v119 offset:32352
	v_sub_f32_e32 v48, v48, v120
	v_sub_f32_e32 v32, v32, v120
	v_sub_f32_e32 v49, v49, v120
	v_sub_f32_e32 v33, v33, v120
	v_sub_f32_e32 v50, v50, v120
	v_sub_f32_e32 v34, v34, v120
	v_sub_f32_e32 v51, v51, v120
	v_sub_f32_e32 v35, v35, v120
	v_sub_f32_e32 v52, v52, v120
	v_sub_f32_e32 v36, v36, v120
	v_sub_f32_e32 v53, v53, v120
	v_sub_f32_e32 v37, v37, v120
	v_sub_f32_e32 v54, v54, v120
	v_sub_f32_e32 v38, v38, v120
	v_sub_f32_e32 v55, v55, v120
	v_sub_f32_e32 v39, v39, v120
	v_sub_f32_e32 v56, v56, v120
	v_sub_f32_e32 v40, v40, v120
	v_sub_f32_e32 v57, v57, v120
	v_sub_f32_e32 v41, v41, v120
	v_sub_f32_e32 v58, v58, v120
	v_sub_f32_e32 v42, v42, v120
	v_sub_f32_e32 v59, v59, v120
	v_sub_f32_e32 v43, v43, v120
	v_sub_f32_e32 v60, v60, v120
	v_sub_f32_e32 v44, v44, v120
	v_sub_f32_e32 v61, v61, v120
	v_sub_f32_e32 v45, v45, v120
	v_sub_f32_e32 v62, v62, v120
	v_sub_f32_e32 v46, v46, v120
	v_sub_f32_e32 v63, v63, v120
	v_sub_f32_e32 v47, v47, v120
	v_exp_f32_e32 v48, v48
	v_exp_f32_e32 v32, v32
	v_exp_f32_e32 v49, v49
	v_exp_f32_e32 v33, v33
	v_exp_f32_e32 v50, v50
	v_exp_f32_e32 v34, v34
	v_exp_f32_e32 v51, v51
	v_exp_f32_e32 v35, v35
	v_exp_f32_e32 v52, v52
	v_exp_f32_e32 v36, v36
	v_exp_f32_e32 v53, v53
	v_exp_f32_e32 v37, v37
	v_exp_f32_e32 v54, v54
	v_exp_f32_e32 v38, v38
	v_exp_f32_e32 v55, v55
	v_exp_f32_e32 v39, v39
	v_exp_f32_e32 v56, v56
	v_exp_f32_e32 v40, v40
	v_exp_f32_e32 v57, v57
	v_exp_f32_e32 v41, v41
	v_exp_f32_e32 v58, v58
	v_exp_f32_e32 v42, v42
	v_exp_f32_e32 v59, v59
	v_exp_f32_e32 v43, v43
	v_exp_f32_e32 v60, v60
	v_exp_f32_e32 v44, v44
	v_exp_f32_e32 v61, v61
	v_exp_f32_e32 v45, v45
	v_exp_f32_e32 v62, v62
	v_exp_f32_e32 v46, v46
	v_exp_f32_e32 v63, v63
	v_exp_f32_e32 v47, v47
	v_cvt_pk_bf16_f32 v122, v48, v49
	v_cvt_pk_bf16_f32 v123, v50, v51
	v_cvt_pk_bf16_f32 v124, v52, v53
	v_cvt_pk_bf16_f32 v125, v54, v55
	v_cvt_pk_bf16_f32 v126, v32, v33
	v_cvt_pk_bf16_f32 v127, v34, v35
	v_cvt_pk_bf16_f32 v128, v36, v37
	v_cvt_pk_bf16_f32 v129, v38, v39
	v_cvt_pk_bf16_f32 v130, v56, v57
	v_cvt_pk_bf16_f32 v131, v58, v59
	v_cvt_pk_bf16_f32 v132, v60, v61
	v_cvt_pk_bf16_f32 v133, v62, v63
	v_cvt_pk_bf16_f32 v150, v40, v41
	v_cvt_pk_bf16_f32 v151, v42, v43
	v_cvt_pk_bf16_f32 v152, v44, v45
	v_cvt_pk_bf16_f32 v153, v46, v47
	s_setprio 1
	s_waitcnt lgkmcnt(7)
	v_mfma_f32_32x32x16_bf16 v[16:31], v[110:113], v[122:125], v[16:31]
	s_waitcnt lgkmcnt(6)
	v_mfma_f32_32x32x16_bf16 v[16:31], v[106:109], v[130:133], v[16:31]
	s_waitcnt lgkmcnt(5)
	v_mfma_f32_32x32x16_bf16 v[16:31], v[102:105], v[126:129], v[16:31]
	s_waitcnt lgkmcnt(4)
	v_mfma_f32_32x32x16_bf16 v[16:31], v[98:101], v[150:153], v[16:31]
	s_setprio 0
	s_setprio 1
	s_waitcnt lgkmcnt(3)
	v_mfma_f32_32x32x16_bf16 v[0:15], v[134:137], v[122:125], v[0:15]
	s_waitcnt lgkmcnt(2)
	v_mfma_f32_32x32x16_bf16 v[0:15], v[138:141], v[130:133], v[0:15]
	s_waitcnt lgkmcnt(1)
	v_mfma_f32_32x32x16_bf16 v[0:15], v[142:145], v[126:129], v[0:15]
	s_waitcnt lgkmcnt(0)
	v_mfma_f32_32x32x16_bf16 v[0:15], v[146:149], v[150:153], v[0:15]
	s_setprio 0
	s_and_b64 vcc, exec, s[0:1]
	s_cbranch_vccnz .LBB0_161
	s_nop 0
	v_lshrrev_b32_e32 v99, 3, v204
	v_lshlrev_b32_e32 v98, 4, v204
	v_and_b32_e32 v98, 0x70, v98
	v_mad_u32_u24 v98, v99, s55, v98
	s_waitcnt vmcnt(1)
	ds_write_b128 v98, v[88:91]
	s_waitcnt vmcnt(0)
	ds_write_b128 v98, v[92:95] offset:9216
	s_branch .LBB0_161

.LBB0_179:
	s_cmp_lt_i32 s24, -5
	v_lshrrev_b32_e32 v6, 3, v204
	v_lshlrev_b32_e32 v5, 4, v204
	v_and_b32_e32 v5, 0x70, v5
	v_mad_u32_u24 v5, v6, s55, v5
	s_waitcnt vmcnt(1)
	ds_write_b128 v5, v[80:83]
	s_waitcnt vmcnt(0)
	ds_write_b128 v5, v[84:87] offset:9216
	s_waitcnt lgkmcnt(0)
	s_barrier
	s_cbranch_scc1 .LBB0_181
	v_mov_b32_e32 v5, v204
	s_nop 0
	v_ashrrev_i32_e32 v6, 3, v5
	v_ashrrev_i32_e32 v7, 31, v6
	v_lshlrev_b64 v[8:9], 7, v[6:7]
	v_lshlrev_b32_e32 v5, 4, v5
	v_lshl_add_u64 v[8:9], s[50:51], 0, v[8:9]
	v_and_b32_e32 v96, 0x70, v5
	v_lshl_add_u64 v[8:9], v[8:9], 0, v[96:97]
	v_add_co_u32_e32 v8, vcc, 0x4000, v8
	v_lshlrev_b64 v[6:7], 10, v[6:7]
	s_nop 0
	v_addc_co_u32_e32 v9, vcc, 0, v9, vcc
	v_lshl_add_u64 v[6:7], s[52:53], 0, v[6:7]
	v_lshl_add_u64 v[6:7], v[6:7], 0, v[96:97]
	global_load_dwordx4 v[80:83], v[8:9], off
	global_load_dwordx4 v[84:87], v[6:7], off offset:256

.LBB0_192:
	s_or_b64 exec, exec, s[40:41]
	s_add_i32 s74, s73, 3
	v_lshrrev_b32_e32 v33, 3, v204
	v_lshlrev_b32_e32 v32, 4, v204
	v_and_b32_e32 v32, 0x70, v32
	v_mad_u32_u24 v32, v33, s55, v32
	s_cmp_ge_i32 s74, s24
	s_waitcnt vmcnt(1)
	ds_write_b128 v32, v[88:91] offset:18432
	s_waitcnt vmcnt(0)
	ds_write_b128 v32, v[92:95] offset:27648
	s_waitcnt lgkmcnt(0)
	s_barrier
	s_cbranch_scc0 .LBB0_195
	s_and_b64 vcc, exec, s[0:1]
	s_cbranch_vccz .LBB0_201

.LBB0_208:
	s_or_b64 exec, exec, s[40:41]
	s_add_i32 s70, s73, 2
	s_cmp_ge_i32 s70, s24
	s_cselect_b64 s[0:1], -1, 0
	s_and_b64 vcc, exec, s[0:1]
	s_cbranch_vccnz .LBB0_210
	s_nop 0
	v_lshrrev_b32_e32 v33, 3, v204
	v_lshlrev_b32_e32 v32, 4, v204
	v_and_b32_e32 v32, 0x70, v32
	v_mad_u32_u24 v32, v33, s55, v32
	s_waitcnt vmcnt(1)
	ds_write_b128 v32, v[80:83]
	s_waitcnt vmcnt(0)
	ds_write_b128 v32, v[84:87] offset:9216

.LBB0_245:
	ds_read_b128 v[196:199], v184 offset:23040
	ds_read_b128 v[200:203], v184 offset:23072
	ds_read_b128 v[206:209], v184 offset:23104
	ds_read_b128 v[216:219], v184 offset:23136
	v_sub_f32_e32 v80, v80, v186
	v_sub_f32_e32 v64, v64, v186
	v_sub_f32_e32 v81, v81, v186
	v_sub_f32_e32 v65, v65, v186
	v_sub_f32_e32 v82, v82, v186
	v_sub_f32_e32 v66, v66, v186
	v_sub_f32_e32 v83, v83, v186
	v_sub_f32_e32 v67, v67, v186
	v_sub_f32_e32 v84, v84, v186
	v_sub_f32_e32 v68, v68, v186
	v_sub_f32_e32 v85, v85, v186
	v_sub_f32_e32 v69, v69, v186
	v_sub_f32_e32 v86, v86, v186
	v_sub_f32_e32 v70, v70, v186
	v_sub_f32_e32 v87, v87, v186
	v_sub_f32_e32 v71, v71, v186
	v_sub_f32_e32 v88, v88, v186
	v_sub_f32_e32 v72, v72, v186
	v_sub_f32_e32 v89, v89, v186
	v_sub_f32_e32 v73, v73, v186
	v_sub_f32_e32 v90, v90, v186
	v_sub_f32_e32 v74, v74, v186
	v_sub_f32_e32 v91, v91, v186
	v_sub_f32_e32 v75, v75, v186
	v_sub_f32_e32 v92, v92, v186
	v_sub_f32_e32 v76, v76, v186
	v_sub_f32_e32 v93, v93, v186
	v_sub_f32_e32 v77, v77, v186
	v_sub_f32_e32 v94, v94, v186
	v_sub_f32_e32 v78, v78, v186
	v_sub_f32_e32 v95, v95, v186
	v_sub_f32_e32 v79, v79, v186
	v_exp_f32_e32 v80, v80
	v_exp_f32_e32 v64, v64
	v_exp_f32_e32 v81, v81
	v_exp_f32_e32 v65, v65
	v_exp_f32_e32 v82, v82
	v_exp_f32_e32 v66, v66
	v_exp_f32_e32 v83, v83
	v_exp_f32_e32 v67, v67
	v_exp_f32_e32 v84, v84
	v_exp_f32_e32 v68, v68
	v_exp_f32_e32 v85, v85
	v_exp_f32_e32 v69, v69
	v_exp_f32_e32 v86, v86
	v_exp_f32_e32 v70, v70
	v_exp_f32_e32 v87, v87
	v_exp_f32_e32 v71, v71
	v_exp_f32_e32 v88, v88
	v_exp_f32_e32 v72, v72
	v_exp_f32_e32 v89, v89
	v_exp_f32_e32 v73, v73
	v_exp_f32_e32 v90, v90
	v_exp_f32_e32 v74, v74
	v_exp_f32_e32 v91, v91
	v_exp_f32_e32 v75, v75
	v_exp_f32_e32 v92, v92
	v_exp_f32_e32 v76, v76
	v_exp_f32_e32 v93, v93
	v_exp_f32_e32 v77, v77
	v_exp_f32_e32 v94, v94
	v_exp_f32_e32 v78, v78
	v_exp_f32_e32 v95, v95
	v_exp_f32_e32 v79, v79
	v_cvt_pk_bf16_f32 v166, v80, v81
	v_cvt_pk_bf16_f32 v167, v82, v83
	v_cvt_pk_bf16_f32 v168, v84, v85
	v_cvt_pk_bf16_f32 v169, v86, v87
	v_cvt_pk_bf16_f32 v188, v64, v65
	v_cvt_pk_bf16_f32 v189, v66, v67
	v_cvt_pk_bf16_f32 v190, v68, v69
	v_cvt_pk_bf16_f32 v191, v70, v71
	v_cvt_pk_bf16_f32 v192, v88, v89
	v_cvt_pk_bf16_f32 v193, v90, v91
	v_cvt_pk_bf16_f32 v194, v92, v93
	v_cvt_pk_bf16_f32 v195, v94, v95
	v_cvt_pk_bf16_f32 v220, v72, v73
	v_cvt_pk_bf16_f32 v221, v74, v75
	v_cvt_pk_bf16_f32 v222, v76, v77
	v_cvt_pk_bf16_f32 v223, v78, v79
	s_setprio 1
	s_waitcnt lgkmcnt(7)
	v_mfma_f32_32x32x16_bf16 v[48:63], v[158:161], v[166:169], v[48:63]
	s_waitcnt lgkmcnt(6)
	v_mfma_f32_32x32x16_bf16 v[48:63], v[154:157], v[192:195], v[48:63]
	s_waitcnt lgkmcnt(5)
	v_mfma_f32_32x32x16_bf16 v[48:63], v[150:153], v[188:191], v[48:63]
	s_waitcnt lgkmcnt(4)
	v_mfma_f32_32x32x16_bf16 v[48:63], v[146:149], v[220:223], v[48:63]
	s_setprio 0
	ds_read_b128 v[146:149], v184 offset:27648
	ds_read_b128 v[150:153], v184 offset:27680
	ds_read_b128 v[154:157], v184 offset:27712
	ds_read_b128 v[158:161], v184 offset:27744
	s_setprio 1
	s_waitcnt lgkmcnt(7)
	v_mfma_f32_32x32x16_bf16 v[32:47], v[196:199], v[166:169], v[32:47]
	s_waitcnt lgkmcnt(6)
	v_mfma_f32_32x32x16_bf16 v[32:47], v[200:203], v[192:195], v[32:47]
	s_waitcnt lgkmcnt(5)
	v_mfma_f32_32x32x16_bf16 v[32:47], v[206:209], v[188:191], v[32:47]
	s_waitcnt lgkmcnt(4)
	v_mfma_f32_32x32x16_bf16 v[32:47], v[216:219], v[220:223], v[32:47]
	s_setprio 0
	ds_read_b128 v[196:199], v184 offset:32256
	ds_read_b128 v[200:203], v184 offset:32288
	ds_read_b128 v[206:209], v184 offset:32320
	ds_read_b128 v[216:219], v184 offset:32352
	s_setprio 1
	s_waitcnt lgkmcnt(7)
	v_mfma_f32_32x32x16_bf16 v[16:31], v[146:149], v[166:169], v[16:31]
	s_waitcnt lgkmcnt(6)
	v_mfma_f32_32x32x16_bf16 v[16:31], v[150:153], v[192:195], v[16:31]
	s_waitcnt lgkmcnt(5)
	v_mfma_f32_32x32x16_bf16 v[16:31], v[154:157], v[188:191], v[16:31]
	s_waitcnt lgkmcnt(4)
	v_mfma_f32_32x32x16_bf16 v[16:31], v[158:161], v[220:223], v[16:31]
	s_setprio 0
	s_setprio 1
	s_waitcnt lgkmcnt(3)
	v_mfma_f32_32x32x16_bf16 v[0:15], v[196:199], v[166:169], v[0:15]
	s_waitcnt lgkmcnt(2)
	v_mfma_f32_32x32x16_bf16 v[0:15], v[200:203], v[192:195], v[0:15]
	s_waitcnt lgkmcnt(1)
	v_mfma_f32_32x32x16_bf16 v[0:15], v[206:209], v[188:191], v[0:15]
	s_waitcnt lgkmcnt(0)
	v_mfma_f32_32x32x16_bf16 v[0:15], v[216:219], v[220:223], v[0:15]
	s_setprio 0
	v_lshrrev_b32_e32 v146, 3, v204
	v_lshlrev_b32_e32 v96, 4, v204
	v_and_b32_e32 v96, 0x70, v96
	v_mad_u32_u24 v148, v146, s55, v96
	v_add_u32_e32 v146, 64, v146
	v_mad_u32_u24 v146, v146, s55, v96
	s_andn2_b64 vcc, exec, s[52:53]
	s_waitcnt vmcnt(3)
	ds_write_b128 v148, v[114:117] offset:36864
	s_waitcnt vmcnt(2)
	ds_write_b128 v148, v[118:121] offset:46080
	s_waitcnt vmcnt(1)
	ds_write_b128 v148, v[122:125] offset:55296
	v_cndmask_b32_e64 v96, 0, 1, s[52:53]
	v_cmp_ne_u32_e64 s[0:1], 1, v96
	s_waitcnt vmcnt(0)
	ds_write_b128 v146, v[126:129] offset:55296
	s_waitcnt lgkmcnt(0)
	s_barrier
	s_cbranch_vccnz .LBB0_247
	s_mov_b64 s[42:43], 0x6000
	v_lshrrev_b32_e32 v126, 3, v204
	v_lshlrev_b32_e32 v96, 4, v204
	v_and_b32_e32 v96, 0x70, v96
	v_lshl_add_u32 v127, v126, 9, v96
	v_lshl_add_u32 v126, v126, 7, v96
	v_add_u32_e32 v128, 0x8000, v127
	v_add_u32_e32 v126, 0x6000, v126
	s_nop 0
	global_load_dwordx4 v[114:117], v126, s[30:31]
	s_nop 0
	global_load_dwordx4 v[118:121], v126, s[40:41]
	s_nop 0
	global_load_dwordx4 v[122:125], v127, s[50:51] offset:384
	s_nop 0
	global_load_dwordx4 v[126:129], v128, s[50:51] offset:384

.LBB0_250:
	ds_read_b128 v[196:199], v184 offset:59904
	ds_read_b128 v[200:203], v184 offset:59936
	ds_read_b128 v[206:209], v184 offset:59968
	ds_read_b128 v[216:219], v184 offset:60000
	v_sub_f32_e32 v80, v80, v187
	v_sub_f32_e32 v64, v64, v187
	v_sub_f32_e32 v81, v81, v187
	v_sub_f32_e32 v65, v65, v187
	v_sub_f32_e32 v82, v82, v187
	v_sub_f32_e32 v66, v66, v187
	v_sub_f32_e32 v83, v83, v187
	v_sub_f32_e32 v67, v67, v187
	v_sub_f32_e32 v84, v84, v187
	v_sub_f32_e32 v68, v68, v187
	v_sub_f32_e32 v85, v85, v187
	v_sub_f32_e32 v69, v69, v187
	v_sub_f32_e32 v86, v86, v187
	v_sub_f32_e32 v70, v70, v187
	v_sub_f32_e32 v87, v87, v187
	v_sub_f32_e32 v71, v71, v187
	v_sub_f32_e32 v88, v88, v187
	v_sub_f32_e32 v72, v72, v187
	v_sub_f32_e32 v89, v89, v187
	v_sub_f32_e32 v73, v73, v187
	v_sub_f32_e32 v90, v90, v187
	v_sub_f32_e32 v74, v74, v187
	v_sub_f32_e32 v91, v91, v187
	v_sub_f32_e32 v75, v75, v187
	v_sub_f32_e32 v92, v92, v187
	v_sub_f32_e32 v76, v76, v187
	v_sub_f32_e32 v93, v93, v187
	v_sub_f32_e32 v77, v77, v187
	v_sub_f32_e32 v94, v94, v187
	v_sub_f32_e32 v78, v78, v187
	v_sub_f32_e32 v95, v95, v187
	v_sub_f32_e32 v79, v79, v187
	v_exp_f32_e32 v80, v80
	v_exp_f32_e32 v64, v64
	v_exp_f32_e32 v81, v81
	v_exp_f32_e32 v65, v65
	v_exp_f32_e32 v82, v82
	v_exp_f32_e32 v66, v66
	v_exp_f32_e32 v83, v83
	v_exp_f32_e32 v67, v67
	v_exp_f32_e32 v84, v84
	v_exp_f32_e32 v68, v68
	v_exp_f32_e32 v85, v85
	v_exp_f32_e32 v69, v69
	v_exp_f32_e32 v86, v86
	v_exp_f32_e32 v70, v70
	v_exp_f32_e32 v87, v87
	v_exp_f32_e32 v71, v71
	v_exp_f32_e32 v88, v88
	v_exp_f32_e32 v72, v72
	v_exp_f32_e32 v89, v89
	v_exp_f32_e32 v73, v73
	v_exp_f32_e32 v90, v90
	v_exp_f32_e32 v74, v74
	v_exp_f32_e32 v91, v91
	v_exp_f32_e32 v75, v75
	v_exp_f32_e32 v92, v92
	v_exp_f32_e32 v76, v76
	v_exp_f32_e32 v93, v93
	v_exp_f32_e32 v77, v77
	v_exp_f32_e32 v94, v94
	v_exp_f32_e32 v78, v78
	v_exp_f32_e32 v95, v95
	v_exp_f32_e32 v79, v79
	v_cvt_pk_bf16_f32 v166, v80, v81
	v_cvt_pk_bf16_f32 v167, v82, v83
	v_cvt_pk_bf16_f32 v168, v84, v85
	v_cvt_pk_bf16_f32 v169, v86, v87
	v_cvt_pk_bf16_f32 v188, v64, v65
	v_cvt_pk_bf16_f32 v189, v66, v67
	v_cvt_pk_bf16_f32 v190, v68, v69
	v_cvt_pk_bf16_f32 v191, v70, v71
	v_cvt_pk_bf16_f32 v192, v88, v89
	v_cvt_pk_bf16_f32 v193, v90, v91
	v_cvt_pk_bf16_f32 v194, v92, v93
	v_cvt_pk_bf16_f32 v195, v94, v95
	v_cvt_pk_bf16_f32 v220, v72, v73
	v_cvt_pk_bf16_f32 v221, v74, v75
	v_cvt_pk_bf16_f32 v222, v76, v77
	v_cvt_pk_bf16_f32 v223, v78, v79
	s_setprio 1
	s_waitcnt lgkmcnt(7)
	v_mfma_f32_32x32x16_bf16 v[48:63], v[158:161], v[166:169], v[48:63]
	s_waitcnt lgkmcnt(6)
	v_mfma_f32_32x32x16_bf16 v[48:63], v[154:157], v[192:195], v[48:63]
	s_waitcnt lgkmcnt(5)
	v_mfma_f32_32x32x16_bf16 v[48:63], v[150:153], v[188:191], v[48:63]
	s_waitcnt lgkmcnt(4)
	v_mfma_f32_32x32x16_bf16 v[48:63], v[146:149], v[220:223], v[48:63]
	s_setprio 0
	ds_read_b128 v[146:149], v184 offset:64512
	ds_read_b128 v[150:153], v184 offset:64544
	ds_read_b128 v[154:157], v184 offset:64576
	ds_read_b128 v[158:161], v184 offset:64608
	s_setprio 1
	s_waitcnt lgkmcnt(7)
	v_mfma_f32_32x32x16_bf16 v[32:47], v[196:199], v[166:169], v[32:47]
	s_waitcnt lgkmcnt(6)
	v_mfma_f32_32x32x16_bf16 v[32:47], v[200:203], v[192:195], v[32:47]
	s_waitcnt lgkmcnt(5)
	v_mfma_f32_32x32x16_bf16 v[32:47], v[206:209], v[188:191], v[32:47]
	s_waitcnt lgkmcnt(4)
	v_mfma_f32_32x32x16_bf16 v[32:47], v[216:219], v[220:223], v[32:47]
	s_setprio 0
	ds_read_b128 v[196:199], v181
	ds_read_b128 v[200:203], v182 offset:32
	ds_read_b128 v[206:209], v182 offset:64
	ds_read_b128 v[216:219], v182 offset:96
	s_setprio 1
	s_waitcnt lgkmcnt(7)
	v_mfma_f32_32x32x16_bf16 v[16:31], v[146:149], v[166:169], v[16:31]
	s_waitcnt lgkmcnt(6)
	v_mfma_f32_32x32x16_bf16 v[16:31], v[150:153], v[192:195], v[16:31]
	s_waitcnt lgkmcnt(5)
	v_mfma_f32_32x32x16_bf16 v[16:31], v[154:157], v[188:191], v[16:31]
	s_waitcnt lgkmcnt(4)
	v_mfma_f32_32x32x16_bf16 v[16:31], v[158:161], v[220:223], v[16:31]
	s_setprio 0
	s_setprio 1
	s_waitcnt lgkmcnt(3)
	v_mfma_f32_32x32x16_bf16 v[0:15], v[196:199], v[166:169], v[0:15]
	s_waitcnt lgkmcnt(2)
	v_mfma_f32_32x32x16_bf16 v[0:15], v[200:203], v[192:195], v[0:15]
	s_waitcnt lgkmcnt(1)
	v_mfma_f32_32x32x16_bf16 v[0:15], v[206:209], v[188:191], v[0:15]
	s_waitcnt lgkmcnt(0)
	v_mfma_f32_32x32x16_bf16 v[0:15], v[216:219], v[220:223], v[0:15]
	s_setprio 0
	s_and_b64 vcc, exec, s[0:1]
	s_cbranch_vccnz .LBB0_241
	v_lshrrev_b32_e32 v146, 3, v204
	v_lshlrev_b32_e32 v147, 4, v204
	v_and_b32_e32 v147, 0x70, v147
	v_mad_u32_u24 v149, v146, s55, v147
	v_add_u32_e32 v146, 64, v146
	v_mad_u32_u24 v146, v146, s55, v147
	s_nop 0
	s_waitcnt vmcnt(3)
	ds_write_b128 v149, v[130:133]
	s_waitcnt vmcnt(2)
	ds_write_b128 v149, v[134:137] offset:9216
	s_waitcnt vmcnt(1)
	ds_write_b128 v149, v[138:141] offset:18432
	s_waitcnt vmcnt(0)
	ds_write_b128 v146, v[142:145] offset:18432
	s_branch .LBB0_241

.LBB0_278:
	ds_read_b128 v[196:199], v184 offset:23040
	ds_read_b128 v[200:203], v184 offset:23072
	ds_read_b128 v[206:209], v184 offset:23104
	ds_read_b128 v[216:219], v184 offset:23136
	v_sub_f32_e32 v80, v80, v187
	v_sub_f32_e32 v64, v64, v187
	v_sub_f32_e32 v81, v81, v187
	v_sub_f32_e32 v65, v65, v187
	v_sub_f32_e32 v82, v82, v187
	v_sub_f32_e32 v66, v66, v187
	v_sub_f32_e32 v83, v83, v187
	v_sub_f32_e32 v67, v67, v187
	v_sub_f32_e32 v84, v84, v187
	v_sub_f32_e32 v68, v68, v187
	v_sub_f32_e32 v85, v85, v187
	v_sub_f32_e32 v69, v69, v187
	v_sub_f32_e32 v86, v86, v187
	v_sub_f32_e32 v70, v70, v187
	v_sub_f32_e32 v87, v87, v187
	v_sub_f32_e32 v71, v71, v187
	v_sub_f32_e32 v88, v88, v187
	v_sub_f32_e32 v72, v72, v187
	v_sub_f32_e32 v89, v89, v187
	v_sub_f32_e32 v73, v73, v187
	v_sub_f32_e32 v90, v90, v187
	v_sub_f32_e32 v74, v74, v187
	v_sub_f32_e32 v91, v91, v187
	v_sub_f32_e32 v75, v75, v187
	v_sub_f32_e32 v92, v92, v187
	v_sub_f32_e32 v76, v76, v187
	v_sub_f32_e32 v93, v93, v187
	v_sub_f32_e32 v77, v77, v187
	v_sub_f32_e32 v94, v94, v187
	v_sub_f32_e32 v78, v78, v187
	v_sub_f32_e32 v95, v95, v187
	v_sub_f32_e32 v79, v79, v187
	v_exp_f32_e32 v80, v80
	v_exp_f32_e32 v64, v64
	v_exp_f32_e32 v81, v81
	v_exp_f32_e32 v65, v65
	v_exp_f32_e32 v82, v82
	v_exp_f32_e32 v66, v66
	v_exp_f32_e32 v83, v83
	v_exp_f32_e32 v67, v67
	v_exp_f32_e32 v84, v84
	v_exp_f32_e32 v68, v68
	v_exp_f32_e32 v85, v85
	v_exp_f32_e32 v69, v69
	v_exp_f32_e32 v86, v86
	v_exp_f32_e32 v70, v70
	v_exp_f32_e32 v87, v87
	v_exp_f32_e32 v71, v71
	v_exp_f32_e32 v88, v88
	v_exp_f32_e32 v72, v72
	v_exp_f32_e32 v89, v89
	v_exp_f32_e32 v73, v73
	v_exp_f32_e32 v90, v90
	v_exp_f32_e32 v74, v74
	v_exp_f32_e32 v91, v91
	v_exp_f32_e32 v75, v75
	v_exp_f32_e32 v92, v92
	v_exp_f32_e32 v76, v76
	v_exp_f32_e32 v93, v93
	v_exp_f32_e32 v77, v77
	v_exp_f32_e32 v94, v94
	v_exp_f32_e32 v78, v78
	v_exp_f32_e32 v95, v95
	v_exp_f32_e32 v79, v79
	v_cvt_pk_bf16_f32 v166, v80, v81
	v_cvt_pk_bf16_f32 v167, v82, v83
	v_cvt_pk_bf16_f32 v168, v84, v85
	v_cvt_pk_bf16_f32 v169, v86, v87
	v_cvt_pk_bf16_f32 v188, v64, v65
	v_cvt_pk_bf16_f32 v189, v66, v67
	v_cvt_pk_bf16_f32 v190, v68, v69
	v_cvt_pk_bf16_f32 v191, v70, v71
	v_cvt_pk_bf16_f32 v192, v88, v89
	v_cvt_pk_bf16_f32 v193, v90, v91
	v_cvt_pk_bf16_f32 v194, v92, v93
	v_cvt_pk_bf16_f32 v195, v94, v95
	v_cvt_pk_bf16_f32 v220, v72, v73
	v_cvt_pk_bf16_f32 v221, v74, v75
	v_cvt_pk_bf16_f32 v222, v76, v77
	v_cvt_pk_bf16_f32 v223, v78, v79
	s_setprio 1
	s_waitcnt lgkmcnt(7)
	v_mfma_f32_32x32x16_bf16 v[48:63], v[158:161], v[166:169], v[48:63]
	s_waitcnt lgkmcnt(6)
	v_mfma_f32_32x32x16_bf16 v[48:63], v[154:157], v[192:195], v[48:63]
	s_waitcnt lgkmcnt(5)
	v_mfma_f32_32x32x16_bf16 v[48:63], v[150:153], v[188:191], v[48:63]
	s_waitcnt lgkmcnt(4)
	v_mfma_f32_32x32x16_bf16 v[48:63], v[146:149], v[220:223], v[48:63]
	s_setprio 0
	ds_read_b128 v[146:149], v184 offset:27648
	ds_read_b128 v[150:153], v184 offset:27680
	ds_read_b128 v[154:157], v184 offset:27712
	ds_read_b128 v[158:161], v184 offset:27744
	s_setprio 1
	s_waitcnt lgkmcnt(7)
	v_mfma_f32_32x32x16_bf16 v[32:47], v[196:199], v[166:169], v[32:47]
	s_waitcnt lgkmcnt(6)
	v_mfma_f32_32x32x16_bf16 v[32:47], v[200:203], v[192:195], v[32:47]
	s_waitcnt lgkmcnt(5)
	v_mfma_f32_32x32x16_bf16 v[32:47], v[206:209], v[188:191], v[32:47]
	s_waitcnt lgkmcnt(4)
	v_mfma_f32_32x32x16_bf16 v[32:47], v[216:219], v[220:223], v[32:47]
	s_setprio 0
	ds_read_b128 v[196:199], v184 offset:32256
	ds_read_b128 v[200:203], v184 offset:32288
	ds_read_b128 v[206:209], v184 offset:32320
	ds_read_b128 v[216:219], v184 offset:32352
	s_setprio 1
	s_waitcnt lgkmcnt(7)
	v_mfma_f32_32x32x16_bf16 v[16:31], v[146:149], v[166:169], v[16:31]
	s_waitcnt lgkmcnt(6)
	v_mfma_f32_32x32x16_bf16 v[16:31], v[150:153], v[192:195], v[16:31]
	s_waitcnt lgkmcnt(5)
	v_mfma_f32_32x32x16_bf16 v[16:31], v[154:157], v[188:191], v[16:31]
	s_waitcnt lgkmcnt(4)
	v_mfma_f32_32x32x16_bf16 v[16:31], v[158:161], v[220:223], v[16:31]
	s_setprio 0
	s_setprio 1
	s_waitcnt lgkmcnt(3)
	v_mfma_f32_32x32x16_bf16 v[0:15], v[196:199], v[166:169], v[0:15]
	s_waitcnt lgkmcnt(2)
	v_mfma_f32_32x32x16_bf16 v[0:15], v[200:203], v[192:195], v[0:15]
	s_waitcnt lgkmcnt(1)
	v_mfma_f32_32x32x16_bf16 v[0:15], v[206:209], v[188:191], v[0:15]
	s_waitcnt lgkmcnt(0)
	v_mfma_f32_32x32x16_bf16 v[0:15], v[216:219], v[220:223], v[0:15]
	s_setprio 0
	v_lshrrev_b32_e32 v146, 3, v204
	v_lshlrev_b32_e32 v96, 4, v204
	v_and_b32_e32 v96, 0x70, v96
	v_mad_u32_u24 v148, v146, s55, v96
	v_add_u32_e32 v146, 64, v146
	v_mad_u32_u24 v146, v146, s55, v96
	s_cmp_gt_u32 s37, 36
	s_waitcnt vmcnt(3)
	ds_write_b128 v148, v[114:117] offset:36864
	s_waitcnt vmcnt(2)
	ds_write_b128 v148, v[118:121] offset:46080
	s_waitcnt vmcnt(1)
	ds_write_b128 v148, v[122:125] offset:55296
	s_waitcnt vmcnt(0)
	ds_write_b128 v146, v[126:129] offset:55296
	s_waitcnt lgkmcnt(0)
	s_barrier
	s_cbranch_scc1 .LBB0_285
	s_cmp_gt_u32 s37, 4
	s_cbranch_scc0 .LBB0_281
	v_mov_b32_e32 v122, v204
	s_add_i32 s24, s37, -5
	s_mov_b64 s[50:51], 0
	s_branch .LBB0_282

.LBB0_288:
	ds_read_b128 v[196:199], v184 offset:59904
	ds_read_b128 v[200:203], v184 offset:59936
	ds_read_b128 v[206:209], v184 offset:59968
	ds_read_b128 v[216:219], v184 offset:60000
	v_sub_f32_e32 v80, v80, v186
	v_sub_f32_e32 v64, v64, v186
	v_sub_f32_e32 v81, v81, v186
	v_sub_f32_e32 v65, v65, v186
	v_sub_f32_e32 v82, v82, v186
	v_sub_f32_e32 v66, v66, v186
	v_sub_f32_e32 v83, v83, v186
	v_sub_f32_e32 v67, v67, v186
	v_sub_f32_e32 v84, v84, v186
	v_sub_f32_e32 v68, v68, v186
	v_sub_f32_e32 v85, v85, v186
	v_sub_f32_e32 v69, v69, v186
	v_sub_f32_e32 v86, v86, v186
	v_sub_f32_e32 v70, v70, v186
	v_sub_f32_e32 v87, v87, v186
	v_sub_f32_e32 v71, v71, v186
	v_sub_f32_e32 v88, v88, v186
	v_sub_f32_e32 v72, v72, v186
	v_sub_f32_e32 v89, v89, v186
	v_sub_f32_e32 v73, v73, v186
	v_sub_f32_e32 v90, v90, v186
	v_sub_f32_e32 v74, v74, v186
	v_sub_f32_e32 v91, v91, v186
	v_sub_f32_e32 v75, v75, v186
	v_sub_f32_e32 v92, v92, v186
	v_sub_f32_e32 v76, v76, v186
	v_sub_f32_e32 v93, v93, v186
	v_sub_f32_e32 v77, v77, v186
	v_sub_f32_e32 v94, v94, v186
	v_sub_f32_e32 v78, v78, v186
	v_sub_f32_e32 v95, v95, v186
	v_sub_f32_e32 v79, v79, v186
	v_exp_f32_e32 v80, v80
	v_exp_f32_e32 v64, v64
	v_exp_f32_e32 v81, v81
	v_exp_f32_e32 v65, v65
	v_exp_f32_e32 v82, v82
	v_exp_f32_e32 v66, v66
	v_exp_f32_e32 v83, v83
	v_exp_f32_e32 v67, v67
	v_exp_f32_e32 v84, v84
	v_exp_f32_e32 v68, v68
	v_exp_f32_e32 v85, v85
	v_exp_f32_e32 v69, v69
	v_exp_f32_e32 v86, v86
	v_exp_f32_e32 v70, v70
	v_exp_f32_e32 v87, v87
	v_exp_f32_e32 v71, v71
	v_exp_f32_e32 v88, v88
	v_exp_f32_e32 v72, v72
	v_exp_f32_e32 v89, v89
	v_exp_f32_e32 v73, v73
	v_exp_f32_e32 v90, v90
	v_exp_f32_e32 v74, v74
	v_exp_f32_e32 v91, v91
	v_exp_f32_e32 v75, v75
	v_exp_f32_e32 v92, v92
	v_exp_f32_e32 v76, v76
	v_exp_f32_e32 v93, v93
	v_exp_f32_e32 v77, v77
	v_exp_f32_e32 v94, v94
	v_exp_f32_e32 v78, v78
	v_exp_f32_e32 v95, v95
	v_exp_f32_e32 v79, v79
	v_cvt_pk_bf16_f32 v166, v80, v81
	v_cvt_pk_bf16_f32 v167, v82, v83
	v_cvt_pk_bf16_f32 v168, v84, v85
	v_cvt_pk_bf16_f32 v169, v86, v87
	v_cvt_pk_bf16_f32 v188, v64, v65
	v_cvt_pk_bf16_f32 v189, v66, v67
	v_cvt_pk_bf16_f32 v190, v68, v69
	v_cvt_pk_bf16_f32 v191, v70, v71
	v_cvt_pk_bf16_f32 v192, v88, v89
	v_cvt_pk_bf16_f32 v193, v90, v91
	v_cvt_pk_bf16_f32 v194, v92, v93
	v_cvt_pk_bf16_f32 v195, v94, v95
	v_cvt_pk_bf16_f32 v220, v72, v73
	v_cvt_pk_bf16_f32 v221, v74, v75
	v_cvt_pk_bf16_f32 v222, v76, v77
	v_cvt_pk_bf16_f32 v223, v78, v79
	s_setprio 1
	s_waitcnt lgkmcnt(7)
	v_mfma_f32_32x32x16_bf16 v[48:63], v[158:161], v[166:169], v[48:63]
	s_waitcnt lgkmcnt(6)
	v_mfma_f32_32x32x16_bf16 v[48:63], v[154:157], v[192:195], v[48:63]
	s_waitcnt lgkmcnt(5)
	v_mfma_f32_32x32x16_bf16 v[48:63], v[150:153], v[188:191], v[48:63]
	s_waitcnt lgkmcnt(4)
	v_mfma_f32_32x32x16_bf16 v[48:63], v[146:149], v[220:223], v[48:63]
	s_setprio 0
	ds_read_b128 v[146:149], v184 offset:64512
	ds_read_b128 v[150:153], v184 offset:64544
	ds_read_b128 v[154:157], v184 offset:64576
	ds_read_b128 v[158:161], v184 offset:64608
	s_setprio 1
	s_waitcnt lgkmcnt(7)
	v_mfma_f32_32x32x16_bf16 v[32:47], v[196:199], v[166:169], v[32:47]
	s_waitcnt lgkmcnt(6)
	v_mfma_f32_32x32x16_bf16 v[32:47], v[200:203], v[192:195], v[32:47]
	s_waitcnt lgkmcnt(5)
	v_mfma_f32_32x32x16_bf16 v[32:47], v[206:209], v[188:191], v[32:47]
	s_waitcnt lgkmcnt(4)
	v_mfma_f32_32x32x16_bf16 v[32:47], v[216:219], v[220:223], v[32:47]
	s_setprio 0
	ds_read_b128 v[196:199], v181
	ds_read_b128 v[200:203], v182 offset:32
	ds_read_b128 v[206:209], v182 offset:64
	ds_read_b128 v[216:219], v182 offset:96
	s_setprio 1
	s_waitcnt lgkmcnt(7)
	v_mfma_f32_32x32x16_bf16 v[16:31], v[146:149], v[166:169], v[16:31]
	s_waitcnt lgkmcnt(6)
	v_mfma_f32_32x32x16_bf16 v[16:31], v[150:153], v[192:195], v[16:31]
	s_waitcnt lgkmcnt(5)
	v_mfma_f32_32x32x16_bf16 v[16:31], v[154:157], v[188:191], v[16:31]
	s_waitcnt lgkmcnt(4)
	v_mfma_f32_32x32x16_bf16 v[16:31], v[158:161], v[220:223], v[16:31]
	s_setprio 0
	s_setprio 1
	s_waitcnt lgkmcnt(3)
	v_mfma_f32_32x32x16_bf16 v[0:15], v[196:199], v[166:169], v[0:15]
	s_waitcnt lgkmcnt(2)
	v_mfma_f32_32x32x16_bf16 v[0:15], v[200:203], v[192:195], v[0:15]
	s_waitcnt lgkmcnt(1)
	v_mfma_f32_32x32x16_bf16 v[0:15], v[206:209], v[188:191], v[0:15]
	s_waitcnt lgkmcnt(0)
	v_mfma_f32_32x32x16_bf16 v[0:15], v[216:219], v[220:223], v[0:15]
	s_setprio 0
	s_cmp_gt_u32 s37, 37
	s_cselect_b64 s[60:61], -1, 0
	s_and_b64 vcc, exec, s[60:61]
	s_cbranch_vccnz .LBB0_290
	v_lshrrev_b32_e32 v146, 3, v204
	v_lshlrev_b32_e32 v96, 4, v204
	v_and_b32_e32 v96, 0x70, v96
	v_mad_u32_u24 v148, v146, s55, v96
	v_add_u32_e32 v146, 64, v146
	v_mad_u32_u24 v146, v146, s55, v96
	s_nop 0
	s_waitcnt vmcnt(3)
	ds_write_b128 v148, v[130:133]
	s_waitcnt vmcnt(2)
	ds_write_b128 v148, v[134:137] offset:9216
	s_waitcnt vmcnt(1)
	ds_write_b128 v148, v[138:141] offset:18432
	s_waitcnt vmcnt(0)
	ds_write_b128 v146, v[142:145] offset:18432
